# hyena: forward/backward filter partial-sum loads issued together and the two block wave-sums interleaved (sample + prompt order loops)
# speedup vs baseline: 1.0092x; 1.0016x over previous
.LBB0_469:
	s_or_b32 s62, s0, s55
	s_or_b32 s64, s62, 0x800
	v_mov_b32_e32 v0, 0
	v_mov_b32_e32 v142, 0
	s_and_saveexec_b64 s[0:1], s[6:7]
	s_mov_b32 s63, s96
	s_mov_b32 s65, s96
	v_lshl_add_u64 v[0:1], s[62:63], 2, v[18:19]
	v_lshl_add_u64 v[142:143], s[64:65], 2, v[18:19]
	global_load_dword v0, v[0:1], off
	global_load_dword v142, v[142:143], off
	s_or_b64 exec, exec, s[0:1]
	v_lshlrev_b32_e32 v144, 2, v192
	v_bitop3_b32 v2, v144, s33, v203 bitop3:0x6c
	s_waitcnt vmcnt(0)
	ds_bpermute_b32 v1, v2, v0
	ds_bpermute_b32 v143, v2, v142
	v_bitop3_b32 v2, v144, 64, v203 bitop3:0x6c
	s_waitcnt lgkmcnt(0)
	v_add_f32_e32 v0, v0, v1
	v_add_f32_e32 v142, v142, v143
	ds_bpermute_b32 v1, v2, v0
	ds_bpermute_b32 v143, v2, v142
	v_bitop3_b32 v2, v144, 32, v203 bitop3:0x6c
	s_waitcnt lgkmcnt(0)
	v_add_f32_e32 v0, v0, v1
	v_add_f32_e32 v142, v142, v143
	ds_bpermute_b32 v1, v2, v0
	ds_bpermute_b32 v143, v2, v142
	v_bitop3_b32 v2, v144, 16, v203 bitop3:0x6c
	s_waitcnt lgkmcnt(0)
	v_add_f32_e32 v0, v0, v1
	v_add_f32_e32 v142, v142, v143
	ds_bpermute_b32 v1, v2, v0
	ds_bpermute_b32 v143, v2, v142
	v_bitop3_b32 v2, v144, 8, v203 bitop3:0x6c
	s_waitcnt lgkmcnt(0)
	v_add_f32_e32 v0, v0, v1
	v_add_f32_e32 v142, v142, v143
	ds_bpermute_b32 v1, v2, v0
	ds_bpermute_b32 v143, v2, v142
	v_bitop3_b32 v2, v144, 4, v203 bitop3:0x6c
	s_waitcnt lgkmcnt(0)
	v_add_f32_e32 v0, v0, v1
	v_add_f32_e32 v142, v142, v143
	ds_bpermute_b32 v1, v2, v0
	ds_bpermute_b32 v143, v2, v142
	s_waitcnt lgkmcnt(0)
	v_add_f32_e32 v0, v0, v1
	v_add_f32_e32 v142, v142, v143
	v_and_b32_e32 v2, 63, v192
	v_cmp_eq_u32_e32 vcc, 0, v2
	s_and_saveexec_b64 s[0:1], vcc
	v_ashrrev_i32_e32 v1, 6, v192
	v_lshl_add_u32 v1, v1, 2, 0
	ds_write_b32 v1, v0 offset:25216
	ds_write_b32 v1, v142 offset:25248
	s_or_b64 exec, exec, s[0:1]
	s_waitcnt lgkmcnt(0)
	s_barrier
	ds_read_b128 v[0:3], v112 offset:25216
	ds_read_b128 v[4:7], v112 offset:25232
	ds_read_b128 v[8:11], v112 offset:25248
	ds_read_b128 v[12:15], v112 offset:25264
	s_mov_b32 s0, 0x358637bd
	s_waitcnt lgkmcnt(3)
	v_mov_b32_e32 v74, v0
	s_mov_b32 s63, s96
	s_waitcnt lgkmcnt(1)
	v_mov_b32_e32 v75, v8
	v_pk_add_f32 v[74:75], v[74:75], 0 op_sel_hi:[1,0]
	v_mov_b32_e32 v8, v1
	v_pk_add_f32 v[0:1], v[74:75], v[8:9]
	v_mov_b32_e32 v8, v2
	v_mov_b32_e32 v9, v10
	v_pk_add_f32 v[0:1], v[0:1], v[8:9]
	v_mov_b32_e32 v10, v3
	v_pk_add_f32 v[0:1], v[0:1], v[10:11]
	v_mov_b32_e32 v2, v4
	s_waitcnt lgkmcnt(0)
	v_mov_b32_e32 v3, v12
	v_pk_add_f32 v[0:1], v[0:1], v[2:3]
	v_mov_b32_e32 v12, v5
	v_pk_add_f32 v[0:1], v[0:1], v[12:13]
	v_mov_b32_e32 v2, v6
	v_mov_b32_e32 v3, v14
	v_pk_add_f32 v[0:1], v[0:1], v[2:3]
	v_mov_b32_e32 v14, v7
	v_pk_add_f32 v[0:1], v[0:1], v[14:15]
	v_readlane_b32 s72, v254, 10
	v_pk_add_f32 v[0:1], v[0:1], s[0:1] op_sel_hi:[1,0]
	v_readlane_b32 s78, v254, 16
	v_div_scale_f32 v2, s[0:1], v1, v1, 1.0
	v_rcp_f32_e32 v3, v2
	v_readlane_b32 s79, v254, 17
	v_readlane_b32 s4, v254, 41
	v_readlane_b32 s5, v254, 42
	v_fma_f32 v4, -v2, v3, 1.0
	v_fmac_f32_e32 v3, v4, v3
	v_div_scale_f32 v4, vcc, 1.0, v1, 1.0
	v_mul_f32_e32 v5, v4, v3
	v_fma_f32 v6, -v2, v5, v4
	v_fmac_f32_e32 v5, v6, v3
	v_fma_f32 v2, -v2, v5, v4
	v_div_fmas_f32 v2, v2, v3, v5
	v_div_fixup_f32 v1, v2, v1, 1.0
	v_div_scale_f32 v2, s[0:1], v0, v0, 1.0
	v_rcp_f32_e32 v3, v2
	s_lshl_b64 s[0:1], s[62:63], 2
	s_add_u32 s0, s78, s0
	s_addc_u32 s1, s79, s1
	v_fma_f32 v4, -v2, v3, 1.0
	v_fmac_f32_e32 v3, v4, v3
	v_div_scale_f32 v4, vcc, 1.0, v0, 1.0
	v_mul_f32_e32 v5, v4, v3
	v_fma_f32 v6, -v2, v5, v4
	v_fmac_f32_e32 v5, v6, v3
	v_fma_f32 v2, -v2, v5, v4
	v_div_fmas_f32 v2, v2, v3, v5
	v_div_fixup_f32 v0, v2, v0, 1.0
	global_load_dword v2, v112, s[0:1]
	s_lshl_b64 s[0:1], s[62:63], 10
	s_add_u32 s62, s4, s0
	s_addc_u32 s63, s5, s1
	s_lshl_b32 s0, s64, 8
	s_mov_b32 s1, s96
	s_lshl_b64 s[0:1], s[0:1], 2
	s_add_u32 s64, s4, s0
	s_addc_u32 s65, s5, s1
	v_mov_b32_e32 v3, 0
	v_mov_b32_e32 v4, 0
	v_readlane_b32 s73, v254, 11
	v_readlane_b32 s74, v254, 12
	v_readlane_b32 s75, v254, 13
	v_readlane_b32 s76, v254, 14
	v_readlane_b32 s77, v254, 15
	v_readlane_b32 s80, v254, 18
	v_readlane_b32 s81, v254, 19
	v_readlane_b32 s82, v254, 20
	v_readlane_b32 s83, v254, 21
	v_readlane_b32 s84, v254, 22
	v_readlane_b32 s85, v254, 23
	v_readlane_b32 s86, v254, 24
	v_readlane_b32 s87, v254, 25
	s_sub_u32 s0, s64, s62
	v_and_b32_e32 v160, 63, v192
	v_lshrrev_b32_e32 v161, 6, v192
	v_lshl_add_u32 v160, v160, 3, v161
	v_sub_u32_e32 v142, 0x100, v160
	v_sub_u32_e32 v161, 0, v142
	v_max_i32_e32 v161, v142, v161
	v_ashrrev_i32_e32 v162, 31, v142
	v_and_b32_e32 v162, s0, v162
	v_lshl_add_u32 v161, v161, 2, v162
	global_load_dword v150, v161, s[62:63]
	v_add_u32_e32 v143, -1, v142
	v_sub_u32_e32 v161, 0, v143
	v_max_i32_e32 v161, v143, v161
	v_ashrrev_i32_e32 v162, 31, v143
	v_and_b32_e32 v162, s0, v162
	v_lshl_add_u32 v161, v161, 2, v162
	global_load_dword v151, v161, s[62:63]
	v_add_u32_e32 v144, -2, v142
	v_sub_u32_e32 v161, 0, v144
	v_max_i32_e32 v161, v144, v161
	v_ashrrev_i32_e32 v162, 31, v144
	v_and_b32_e32 v162, s0, v162
	v_lshl_add_u32 v161, v161, 2, v162
	global_load_dword v152, v161, s[62:63]
	v_add_u32_e32 v145, -3, v142
	v_sub_u32_e32 v161, 0, v145
	v_max_i32_e32 v161, v145, v161
	v_ashrrev_i32_e32 v162, 31, v145
	v_and_b32_e32 v162, s0, v162
	v_lshl_add_u32 v161, v161, 2, v162
	global_load_dword v153, v161, s[62:63]
	v_add_u32_e32 v146, -4, v142
	v_sub_u32_e32 v161, 0, v146
	v_max_i32_e32 v161, v146, v161
	v_ashrrev_i32_e32 v162, 31, v146
	v_and_b32_e32 v162, s0, v162
	v_lshl_add_u32 v161, v161, 2, v162
	global_load_dword v154, v161, s[62:63]
	v_add_u32_e32 v147, -5, v142
	v_sub_u32_e32 v161, 0, v147
	v_max_i32_e32 v161, v147, v161
	v_ashrrev_i32_e32 v162, 31, v147
	v_and_b32_e32 v162, s0, v162
	v_lshl_add_u32 v161, v161, 2, v162
	global_load_dword v155, v161, s[62:63]
	v_add_u32_e32 v148, -6, v142
	v_sub_u32_e32 v161, 0, v148
	v_max_i32_e32 v161, v148, v161
	v_ashrrev_i32_e32 v162, 31, v148
	v_and_b32_e32 v162, s0, v162
	v_lshl_add_u32 v161, v161, 2, v162
	global_load_dword v156, v161, s[62:63]
	v_add_u32_e32 v149, -7, v142
	v_sub_u32_e32 v161, 0, v149
	v_max_i32_e32 v161, v149, v161
	v_ashrrev_i32_e32 v162, 31, v149
	v_and_b32_e32 v162, s0, v162
	v_lshl_add_u32 v161, v161, 2, v162
	global_load_dword v157, v161, s[62:63]
	global_load_dword v158, v112, s[62:63]
	global_load_dword v159, v112, s[64:65]
	s_waitcnt vmcnt(0)
	v_mul_f32_e32 v158, v0, v158
	v_mul_f32_e32 v159, v1, v159
	v_add_f32_e32 v158, v158, v159
	v_add_f32_e32 v158, v2, v158
	v_cmp_lt_i32_e32 vcc, 0, v142
	v_add_u32_e32 v161, 0xff, v142
	s_nop 0
	v_cndmask_b32_e32 v160, v1, v0, vcc
	v_cmp_eq_u32_e32 vcc, 0, v142
	v_mul_f32_e32 v150, v160, v150
	s_nop 0
	v_cndmask_b32_e32 v150, v150, v158, vcc
	v_cmp_gt_u32_e32 vcc, 0x1ff, v161
	s_nop 1
	v_cndmask_b32_e32 v150, 0, v150, vcc
	v_cmp_lt_i32_e32 vcc, 0, v143
	v_add_u32_e32 v161, 0xff, v143
	s_nop 0
	v_cndmask_b32_e32 v160, v1, v0, vcc
	v_cmp_eq_u32_e32 vcc, 0, v143
	v_mul_f32_e32 v151, v160, v151
	s_nop 0
	v_cndmask_b32_e32 v151, v151, v158, vcc
	v_cmp_gt_u32_e32 vcc, 0x1ff, v161
	s_nop 1
	v_cndmask_b32_e32 v151, 0, v151, vcc
	v_cmp_lt_i32_e32 vcc, 0, v144
	v_add_u32_e32 v161, 0xff, v144
	s_nop 0
	v_cndmask_b32_e32 v160, v1, v0, vcc
	v_cmp_eq_u32_e32 vcc, 0, v144
	v_mul_f32_e32 v152, v160, v152
	s_nop 0
	v_cndmask_b32_e32 v152, v152, v158, vcc
	v_cmp_gt_u32_e32 vcc, 0x1ff, v161
	s_nop 1
	v_cndmask_b32_e32 v152, 0, v152, vcc
	v_cmp_lt_i32_e32 vcc, 0, v145
	v_add_u32_e32 v161, 0xff, v145
	s_nop 0
	v_cndmask_b32_e32 v160, v1, v0, vcc
	v_cmp_eq_u32_e32 vcc, 0, v145
	v_mul_f32_e32 v153, v160, v153
	s_nop 0
	v_cndmask_b32_e32 v153, v153, v158, vcc
	v_cmp_gt_u32_e32 vcc, 0x1ff, v161
	s_nop 1
	v_cndmask_b32_e32 v153, 0, v153, vcc
	v_cmp_lt_i32_e32 vcc, 0, v146
	v_add_u32_e32 v161, 0xff, v146
	s_nop 0
	v_cndmask_b32_e32 v160, v1, v0, vcc
	v_cmp_eq_u32_e32 vcc, 0, v146
	v_mul_f32_e32 v154, v160, v154
	s_nop 0
	v_cndmask_b32_e32 v154, v154, v158, vcc
	v_cmp_gt_u32_e32 vcc, 0x1ff, v161
	s_nop 1
	v_cndmask_b32_e32 v154, 0, v154, vcc
	v_cmp_lt_i32_e32 vcc, 0, v147
	v_add_u32_e32 v161, 0xff, v147
	s_nop 0
	v_cndmask_b32_e32 v160, v1, v0, vcc
	v_cmp_eq_u32_e32 vcc, 0, v147
	v_mul_f32_e32 v155, v160, v155
	s_nop 0
	v_cndmask_b32_e32 v155, v155, v158, vcc
	v_cmp_gt_u32_e32 vcc, 0x1ff, v161
	s_nop 1
	v_cndmask_b32_e32 v155, 0, v155, vcc
	v_cmp_lt_i32_e32 vcc, 0, v148
	v_add_u32_e32 v161, 0xff, v148
	s_nop 0
	v_cndmask_b32_e32 v160, v1, v0, vcc
	v_cmp_eq_u32_e32 vcc, 0, v148
	v_mul_f32_e32 v156, v160, v156
	s_nop 0
	v_cndmask_b32_e32 v156, v156, v158, vcc
	v_cmp_gt_u32_e32 vcc, 0x1ff, v161
	s_nop 1
	v_cndmask_b32_e32 v156, 0, v156, vcc
	v_cmp_lt_i32_e32 vcc, 0, v149
	v_add_u32_e32 v161, 0xff, v149
	s_nop 0
	v_cndmask_b32_e32 v160, v1, v0, vcc
	v_cmp_eq_u32_e32 vcc, 0, v149
	v_mul_f32_e32 v157, v160, v157
	s_nop 0
	v_cndmask_b32_e32 v157, v157, v158, vcc
	v_cmp_gt_u32_e32 vcc, 0x1ff, v161
	s_nop 1
	v_cndmask_b32_e32 v157, 0, v157, vcc
	v_cvt_pk_bf16_f32 v0, v150, v151
	v_cvt_pk_bf16_f32 v1, v152, v153
	v_cvt_pk_bf16_f32 v2, v154, v155
	v_cvt_pk_bf16_f32 v3, v156, v157
	s_and_b64 vcc, exec, s[60:61]
	ds_write_b128 v73, v[0:3]
	s_cbranch_vccz .LBB0_559
	global_load_dwordx4 v[0:3], v[52:53], off
	global_load_dwordx4 v[4:7], v[54:55], off
	v_add_u32_e32 v8, v17, v67
	v_add_u32_e32 v9, v17, v64
	s_waitcnt vmcnt(1)
	ds_write_b128 v8, v[0:3] offset:8320
	s_waitcnt vmcnt(0)
	ds_write_b128 v9, v[4:7] offset:8320

.LBB0_565:
	s_or_b32 s12, s0, s55
	s_or_b32 s50, s12, 0x800
	v_mov_b32_e32 v0, 0
	v_mov_b32_e32 v142, 0
	s_and_saveexec_b64 s[0:1], s[6:7]
	s_mov_b32 s13, s2
	s_mov_b32 s51, s2
	v_lshl_add_u64 v[0:1], s[12:13], 2, v[18:19]
	v_lshl_add_u64 v[142:143], s[50:51], 2, v[18:19]
	global_load_dword v0, v[0:1], off
	global_load_dword v142, v[142:143], off
	s_or_b64 exec, exec, s[0:1]
	v_lshlrev_b32_e32 v144, 2, v192
	v_bitop3_b32 v2, v144, s33, v203 bitop3:0x6c
	s_waitcnt vmcnt(0)
	ds_bpermute_b32 v1, v2, v0
	ds_bpermute_b32 v143, v2, v142
	v_bitop3_b32 v2, v144, 64, v203 bitop3:0x6c
	s_waitcnt lgkmcnt(0)
	v_add_f32_e32 v0, v0, v1
	v_add_f32_e32 v142, v142, v143
	ds_bpermute_b32 v1, v2, v0
	ds_bpermute_b32 v143, v2, v142
	v_bitop3_b32 v2, v144, 32, v203 bitop3:0x6c
	s_waitcnt lgkmcnt(0)
	v_add_f32_e32 v0, v0, v1
	v_add_f32_e32 v142, v142, v143
	ds_bpermute_b32 v1, v2, v0
	ds_bpermute_b32 v143, v2, v142
	v_bitop3_b32 v2, v144, 16, v203 bitop3:0x6c
	s_waitcnt lgkmcnt(0)
	v_add_f32_e32 v0, v0, v1
	v_add_f32_e32 v142, v142, v143
	ds_bpermute_b32 v1, v2, v0
	ds_bpermute_b32 v143, v2, v142
	v_bitop3_b32 v2, v144, 8, v203 bitop3:0x6c
	s_waitcnt lgkmcnt(0)
	v_add_f32_e32 v0, v0, v1
	v_add_f32_e32 v142, v142, v143
	ds_bpermute_b32 v1, v2, v0
	ds_bpermute_b32 v143, v2, v142
	v_bitop3_b32 v2, v144, 4, v203 bitop3:0x6c
	s_waitcnt lgkmcnt(0)
	v_add_f32_e32 v0, v0, v1
	v_add_f32_e32 v142, v142, v143
	ds_bpermute_b32 v1, v2, v0
	ds_bpermute_b32 v143, v2, v142
	s_waitcnt lgkmcnt(0)
	v_add_f32_e32 v0, v0, v1
	v_add_f32_e32 v142, v142, v143
	v_and_b32_e32 v2, 63, v192
	v_cmp_eq_u32_e32 vcc, 0, v2
	s_and_saveexec_b64 s[0:1], vcc
	v_ashrrev_i32_e32 v1, 6, v192
	v_lshl_add_u32 v1, v1, 2, 0
	v_add_u32_e32 v1, 0x24a80, v1
	ds_write_b32 v1, v0
	ds_write_b32 v1, v142 offset:32
	s_or_b64 exec, exec, s[0:1]
	s_add_i32 s0, 0, 0x24a80
	v_mov_b32_e32 v12, s0
	s_waitcnt lgkmcnt(0)
	s_barrier
	ds_read_b128 v[0:3], v12
	ds_read_b128 v[4:7], v12 offset:16
	ds_read_b128 v[8:11], v12 offset:32
	ds_read_b128 v[12:15], v12 offset:48
	s_mov_b32 s0, 0x358637bd
	s_waitcnt lgkmcnt(3)
	v_mov_b32_e32 v96, v0
	s_mov_b32 s4, 0
	s_waitcnt lgkmcnt(1)
	v_mov_b32_e32 v97, v8
	v_pk_add_f32 v[96:97], v[96:97], 0 op_sel_hi:[1,0]
	v_mov_b32_e32 v8, v1
	v_pk_add_f32 v[0:1], v[96:97], v[8:9]
	v_mov_b32_e32 v8, v2
	v_mov_b32_e32 v9, v10
	v_pk_add_f32 v[0:1], v[0:1], v[8:9]
	v_mov_b32_e32 v10, v3
	v_pk_add_f32 v[0:1], v[0:1], v[10:11]
	v_mov_b32_e32 v2, v4
	s_waitcnt lgkmcnt(0)
	v_mov_b32_e32 v3, v12
	v_pk_add_f32 v[0:1], v[0:1], v[2:3]
	v_mov_b32_e32 v12, v5
	v_pk_add_f32 v[0:1], v[0:1], v[12:13]
	v_mov_b32_e32 v2, v6
	v_mov_b32_e32 v3, v14
	v_pk_add_f32 v[0:1], v[0:1], v[2:3]
	v_mov_b32_e32 v14, v7
	v_pk_add_f32 v[0:1], v[0:1], v[14:15]
	s_movk_i32 s5, 0x5eed
	v_pk_add_f32 v[0:1], v[0:1], s[0:1] op_sel_hi:[1,0]
	s_mov_b32 s13, s4
	v_div_scale_f32 v2, s[0:1], v1, v1, 1.0
	v_rcp_f32_e32 v3, v2
	v_readlane_b32 s16, v254, 10
	v_readlane_b32 s22, v254, 16
	v_readlane_b32 s23, v254, 17
	v_fma_f32 v4, -v2, v3, 1.0
	v_fmac_f32_e32 v3, v4, v3
	v_div_scale_f32 v4, vcc, 1.0, v1, 1.0
	v_mul_f32_e32 v5, v4, v3
	v_fma_f32 v6, -v2, v5, v4
	v_fmac_f32_e32 v5, v6, v3
	v_fma_f32 v2, -v2, v5, v4
	v_div_fmas_f32 v2, v2, v3, v5
	v_div_fixup_f32 v1, v2, v1, 1.0
	v_div_scale_f32 v2, s[0:1], v0, v0, 1.0
	v_rcp_f32_e32 v3, v2
	s_lshl_b64 s[0:1], s[12:13], 2
	s_add_u32 s0, s22, s0
	s_addc_u32 s1, s23, s1
	v_fma_f32 v4, -v2, v3, 1.0
	v_fmac_f32_e32 v3, v4, v3
	v_div_scale_f32 v4, vcc, 1.0, v0, 1.0
	v_mul_f32_e32 v5, v4, v3
	v_fma_f32 v6, -v2, v5, v4
	v_fmac_f32_e32 v5, v6, v3
	v_fma_f32 v2, -v2, v5, v4
	global_load_dword v4, v112, s[0:1]
	s_lshl_b64 s[0:1], s[12:13], 14
	s_add_u32 s80, s91, s0
	s_addc_u32 s81, s54, s1
	s_lshl_b32 s0, s50, 12
	s_mov_b32 s1, s4
	s_lshl_b64 s[0:1], s[0:1], 2
	v_div_fmas_f32 v2, v2, v3, v5
	s_add_u32 s12, s91, s0
	v_div_fixup_f32 v0, v2, v0, 1.0
	s_mov_b32 s2, 0
	s_addc_u32 s13, s54, s1
	v_mov_b32_e32 v2, 0
	v_mov_b32_e32 v3, 0
	v_readlane_b32 s17, v254, 11
	v_readlane_b32 s18, v254, 12
	v_readlane_b32 s19, v254, 13
	v_readlane_b32 s20, v254, 14
	v_readlane_b32 s21, v254, 15
	v_readlane_b32 s24, v254, 18
	v_readlane_b32 s25, v254, 19
	v_readlane_b32 s26, v254, 20
	v_readlane_b32 s27, v254, 21
	v_readlane_b32 s28, v254, 22
	v_readlane_b32 s29, v254, 23
	v_readlane_b32 s30, v254, 24
	v_readlane_b32 s31, v254, 25
	s_movk_i32 s3, 0x5eed
	s_sub_u32 s0, s12, s80
	v_lshlrev_b32_e32 v248, 4, v192
	v_sub_u32_e32 v213, 0x1000, v248
	v_sub_u32_e32 v249, 0, v213
	v_max_i32_e32 v249, v213, v249
	v_ashrrev_i32_e32 v250, 31, v213
	v_and_b32_e32 v250, s0, v250
	v_lshl_add_u32 v249, v249, 2, v250
	global_load_dword v95, v249, s[80:81]
	v_add_u32_e32 v214, -1, v213
	v_sub_u32_e32 v249, 0, v214
	v_max_i32_e32 v249, v214, v249
	v_ashrrev_i32_e32 v250, 31, v214
	v_and_b32_e32 v250, s0, v250
	v_lshl_add_u32 v249, v249, 2, v250
	global_load_dword v96, v249, s[80:81]
	v_add_u32_e32 v215, -2, v213
	v_sub_u32_e32 v249, 0, v215
	v_max_i32_e32 v249, v215, v249
	v_ashrrev_i32_e32 v250, 31, v215
	v_and_b32_e32 v250, s0, v250
	v_lshl_add_u32 v249, v249, 2, v250
	global_load_dword v97, v249, s[80:81]
	v_add_u32_e32 v216, -3, v213
	v_sub_u32_e32 v249, 0, v216
	v_max_i32_e32 v249, v216, v249
	v_ashrrev_i32_e32 v250, 31, v216
	v_and_b32_e32 v250, s0, v250
	v_lshl_add_u32 v249, v249, 2, v250
	global_load_dword v98, v249, s[80:81]
	v_add_u32_e32 v217, -4, v213
	v_sub_u32_e32 v249, 0, v217
	v_max_i32_e32 v249, v217, v249
	v_ashrrev_i32_e32 v250, 31, v217
	v_and_b32_e32 v250, s0, v250
	v_lshl_add_u32 v249, v249, 2, v250
	global_load_dword v99, v249, s[80:81]
	v_add_u32_e32 v218, -5, v213
	v_sub_u32_e32 v249, 0, v218
	v_max_i32_e32 v249, v218, v249
	v_ashrrev_i32_e32 v250, 31, v218
	v_and_b32_e32 v250, s0, v250
	v_lshl_add_u32 v249, v249, 2, v250
	global_load_dword v100, v249, s[80:81]
	v_add_u32_e32 v219, -6, v213
	v_sub_u32_e32 v249, 0, v219
	v_max_i32_e32 v249, v219, v249
	v_ashrrev_i32_e32 v250, 31, v219
	v_and_b32_e32 v250, s0, v250
	v_lshl_add_u32 v249, v249, 2, v250
	global_load_dword v101, v249, s[80:81]
	v_add_u32_e32 v220, -7, v213
	v_sub_u32_e32 v249, 0, v220
	v_max_i32_e32 v249, v220, v249
	v_ashrrev_i32_e32 v250, 31, v220
	v_and_b32_e32 v250, s0, v250
	v_lshl_add_u32 v249, v249, 2, v250
	global_load_dword v102, v249, s[80:81]
	v_add_u32_e32 v221, -8, v213
	v_sub_u32_e32 v249, 0, v221
	v_max_i32_e32 v249, v221, v249
	v_ashrrev_i32_e32 v250, 31, v221
	v_and_b32_e32 v250, s0, v250
	v_lshl_add_u32 v249, v249, 2, v250
	global_load_dword v103, v249, s[80:81]
	v_add_u32_e32 v222, -9, v213
	v_sub_u32_e32 v249, 0, v222
	v_max_i32_e32 v249, v222, v249
	v_ashrrev_i32_e32 v250, 31, v222
	v_and_b32_e32 v250, s0, v250
	v_lshl_add_u32 v249, v249, 2, v250
	global_load_dword v104, v249, s[80:81]
	v_add_u32_e32 v223, -10, v213
	v_sub_u32_e32 v249, 0, v223
	v_max_i32_e32 v249, v223, v249
	v_ashrrev_i32_e32 v250, 31, v223
	v_and_b32_e32 v250, s0, v250
	v_lshl_add_u32 v249, v249, 2, v250
	global_load_dword v105, v249, s[80:81]
	v_add_u32_e32 v224, -11, v213
	v_sub_u32_e32 v249, 0, v224
	v_max_i32_e32 v249, v224, v249
	v_ashrrev_i32_e32 v250, 31, v224
	v_and_b32_e32 v250, s0, v250
	v_lshl_add_u32 v249, v249, 2, v250
	global_load_dword v106, v249, s[80:81]
	v_add_u32_e32 v225, -12, v213
	v_sub_u32_e32 v249, 0, v225
	v_max_i32_e32 v249, v225, v249
	v_ashrrev_i32_e32 v250, 31, v225
	v_and_b32_e32 v250, s0, v250
	v_lshl_add_u32 v249, v249, 2, v250
	global_load_dword v107, v249, s[80:81]
	v_add_u32_e32 v226, -13, v213
	v_sub_u32_e32 v249, 0, v226
	v_max_i32_e32 v249, v226, v249
	v_ashrrev_i32_e32 v250, 31, v226
	v_and_b32_e32 v250, s0, v250
	v_lshl_add_u32 v249, v249, 2, v250
	global_load_dword v108, v249, s[80:81]
	v_add_u32_e32 v227, -14, v213
	v_sub_u32_e32 v249, 0, v227
	v_max_i32_e32 v249, v227, v249
	v_ashrrev_i32_e32 v250, 31, v227
	v_and_b32_e32 v250, s0, v250
	v_lshl_add_u32 v249, v249, 2, v250
	global_load_dword v109, v249, s[80:81]
	v_add_u32_e32 v228, -15, v213
	v_sub_u32_e32 v249, 0, v228
	v_max_i32_e32 v249, v228, v249
	v_ashrrev_i32_e32 v250, 31, v228
	v_and_b32_e32 v250, s0, v250
	v_lshl_add_u32 v249, v249, 2, v250
	global_load_dword v110, v249, s[80:81]
	v_add_u32_e32 v229, -16, v213
	v_sub_u32_e32 v249, 0, v229
	v_max_i32_e32 v249, v229, v249
	v_ashrrev_i32_e32 v250, 31, v229
	v_and_b32_e32 v250, s0, v250
	v_lshl_add_u32 v249, v249, 2, v250
	global_load_dword v111, v249, s[80:81]
	v_add_u32_e32 v230, -17, v213
	v_sub_u32_e32 v249, 0, v230
	v_max_i32_e32 v249, v230, v249
	v_ashrrev_i32_e32 v250, 31, v230
	v_and_b32_e32 v250, s0, v250
	v_lshl_add_u32 v249, v249, 2, v250
	global_load_dword v122, v249, s[80:81]
	v_add_u32_e32 v231, -18, v213
	v_sub_u32_e32 v249, 0, v231
	v_max_i32_e32 v249, v231, v249
	v_ashrrev_i32_e32 v250, 31, v231
	v_and_b32_e32 v250, s0, v250
	v_lshl_add_u32 v249, v249, 2, v250
	global_load_dword v123, v249, s[80:81]
	v_add_u32_e32 v232, -19, v213
	v_sub_u32_e32 v249, 0, v232
	v_max_i32_e32 v249, v232, v249
	v_ashrrev_i32_e32 v250, 31, v232
	v_and_b32_e32 v250, s0, v250
	v_lshl_add_u32 v249, v249, 2, v250
	global_load_dword v124, v249, s[80:81]
	v_add_u32_e32 v233, -20, v213
	v_sub_u32_e32 v249, 0, v233
	v_max_i32_e32 v249, v233, v249
	v_ashrrev_i32_e32 v250, 31, v233
	v_and_b32_e32 v250, s0, v250
	v_lshl_add_u32 v249, v249, 2, v250
	global_load_dword v125, v249, s[80:81]
	v_add_u32_e32 v234, -21, v213
	v_sub_u32_e32 v249, 0, v234
	v_max_i32_e32 v249, v234, v249
	v_ashrrev_i32_e32 v250, 31, v234
	v_and_b32_e32 v250, s0, v250
	v_lshl_add_u32 v249, v249, 2, v250
	global_load_dword v126, v249, s[80:81]
	v_add_u32_e32 v235, -22, v213
	v_sub_u32_e32 v249, 0, v235
	v_max_i32_e32 v249, v235, v249
	v_ashrrev_i32_e32 v250, 31, v235
	v_and_b32_e32 v250, s0, v250
	v_lshl_add_u32 v249, v249, 2, v250
	global_load_dword v127, v249, s[80:81]
	global_load_dword v246, v112, s[80:81]
	global_load_dword v247, v112, s[12:13]
	v_lshlrev_b32_e32 v251, 5, v192
	v_add_u32_e32 v162, 0x100d0, v251
	s_waitcnt vmcnt(0)
	v_mul_f32_e32 v246, v0, v246
	v_mul_f32_e32 v247, v1, v247
	v_add_f32_e32 v246, v246, v247
	v_add_f32_e32 v246, v4, v246
	v_cmp_lt_i32_e32 vcc, 0, v213
	v_add_u32_e32 v249, 0xfff, v213
	s_nop 0
	v_cndmask_b32_e32 v248, v1, v0, vcc
	v_cmp_eq_u32_e32 vcc, 0, v213
	v_mul_f32_e32 v95, v248, v95
	s_nop 0
	v_cndmask_b32_e32 v95, v95, v246, vcc
	v_cmp_gt_u32_e32 vcc, 0x1fff, v249
	s_nop 1
	v_cndmask_b32_e32 v95, 0, v95, vcc
	v_cmp_lt_i32_e32 vcc, 0, v214
	v_add_u32_e32 v249, 0xfff, v214
	s_nop 0
	v_cndmask_b32_e32 v248, v1, v0, vcc
	v_cmp_eq_u32_e32 vcc, 0, v214
	v_mul_f32_e32 v96, v248, v96
	s_nop 0
	v_cndmask_b32_e32 v96, v96, v246, vcc
	v_cmp_gt_u32_e32 vcc, 0x1fff, v249
	s_nop 1
	v_cndmask_b32_e32 v96, 0, v96, vcc
	v_cmp_lt_i32_e32 vcc, 0, v215
	v_add_u32_e32 v249, 0xfff, v215
	s_nop 0
	v_cndmask_b32_e32 v248, v1, v0, vcc
	v_cmp_eq_u32_e32 vcc, 0, v215
	v_mul_f32_e32 v97, v248, v97
	s_nop 0
	v_cndmask_b32_e32 v97, v97, v246, vcc
	v_cmp_gt_u32_e32 vcc, 0x1fff, v249
	s_nop 1
	v_cndmask_b32_e32 v97, 0, v97, vcc
	v_cmp_lt_i32_e32 vcc, 0, v216
	v_add_u32_e32 v249, 0xfff, v216
	s_nop 0
	v_cndmask_b32_e32 v248, v1, v0, vcc
	v_cmp_eq_u32_e32 vcc, 0, v216
	v_mul_f32_e32 v98, v248, v98
	s_nop 0
	v_cndmask_b32_e32 v98, v98, v246, vcc
	v_cmp_gt_u32_e32 vcc, 0x1fff, v249
	s_nop 1
	v_cndmask_b32_e32 v98, 0, v98, vcc
	v_cmp_lt_i32_e32 vcc, 0, v217
	v_add_u32_e32 v249, 0xfff, v217
	s_nop 0
	v_cndmask_b32_e32 v248, v1, v0, vcc
	v_cmp_eq_u32_e32 vcc, 0, v217
	v_mul_f32_e32 v99, v248, v99
	s_nop 0
	v_cndmask_b32_e32 v99, v99, v246, vcc
	v_cmp_gt_u32_e32 vcc, 0x1fff, v249
	s_nop 1
	v_cndmask_b32_e32 v99, 0, v99, vcc
	v_cmp_lt_i32_e32 vcc, 0, v218
	v_add_u32_e32 v249, 0xfff, v218
	s_nop 0
	v_cndmask_b32_e32 v248, v1, v0, vcc
	v_cmp_eq_u32_e32 vcc, 0, v218
	v_mul_f32_e32 v100, v248, v100
	s_nop 0
	v_cndmask_b32_e32 v100, v100, v246, vcc
	v_cmp_gt_u32_e32 vcc, 0x1fff, v249
	s_nop 1
	v_cndmask_b32_e32 v100, 0, v100, vcc
	v_cmp_lt_i32_e32 vcc, 0, v219
	v_add_u32_e32 v249, 0xfff, v219
	s_nop 0
	v_cndmask_b32_e32 v248, v1, v0, vcc
	v_cmp_eq_u32_e32 vcc, 0, v219
	v_mul_f32_e32 v101, v248, v101
	s_nop 0
	v_cndmask_b32_e32 v101, v101, v246, vcc
	v_cmp_gt_u32_e32 vcc, 0x1fff, v249
	s_nop 1
	v_cndmask_b32_e32 v101, 0, v101, vcc
	v_cmp_lt_i32_e32 vcc, 0, v220
	v_add_u32_e32 v249, 0xfff, v220
	s_nop 0
	v_cndmask_b32_e32 v248, v1, v0, vcc
	v_cmp_eq_u32_e32 vcc, 0, v220
	v_mul_f32_e32 v102, v248, v102
	s_nop 0
	v_cndmask_b32_e32 v102, v102, v246, vcc
	v_cmp_gt_u32_e32 vcc, 0x1fff, v249
	s_nop 1
	v_cndmask_b32_e32 v102, 0, v102, vcc
	v_cmp_lt_i32_e32 vcc, 0, v221
	v_add_u32_e32 v249, 0xfff, v221
	s_nop 0
	v_cndmask_b32_e32 v248, v1, v0, vcc
	v_cmp_eq_u32_e32 vcc, 0, v221
	v_mul_f32_e32 v103, v248, v103
	s_nop 0
	v_cndmask_b32_e32 v103, v103, v246, vcc
	v_cmp_gt_u32_e32 vcc, 0x1fff, v249
	s_nop 1
	v_cndmask_b32_e32 v103, 0, v103, vcc
	v_cmp_lt_i32_e32 vcc, 0, v222
	v_add_u32_e32 v249, 0xfff, v222
	s_nop 0
	v_cndmask_b32_e32 v248, v1, v0, vcc
	v_cmp_eq_u32_e32 vcc, 0, v222
	v_mul_f32_e32 v104, v248, v104
	s_nop 0
	v_cndmask_b32_e32 v104, v104, v246, vcc
	v_cmp_gt_u32_e32 vcc, 0x1fff, v249
	s_nop 1
	v_cndmask_b32_e32 v104, 0, v104, vcc
	v_cmp_lt_i32_e32 vcc, 0, v223
	v_add_u32_e32 v249, 0xfff, v223
	s_nop 0
	v_cndmask_b32_e32 v248, v1, v0, vcc
	v_cmp_eq_u32_e32 vcc, 0, v223
	v_mul_f32_e32 v105, v248, v105
	s_nop 0
	v_cndmask_b32_e32 v105, v105, v246, vcc
	v_cmp_gt_u32_e32 vcc, 0x1fff, v249
	s_nop 1
	v_cndmask_b32_e32 v105, 0, v105, vcc
	v_cmp_lt_i32_e32 vcc, 0, v224
	v_add_u32_e32 v249, 0xfff, v224
	s_nop 0
	v_cndmask_b32_e32 v248, v1, v0, vcc
	v_cmp_eq_u32_e32 vcc, 0, v224
	v_mul_f32_e32 v106, v248, v106
	s_nop 0
	v_cndmask_b32_e32 v106, v106, v246, vcc
	v_cmp_gt_u32_e32 vcc, 0x1fff, v249
	s_nop 1
	v_cndmask_b32_e32 v106, 0, v106, vcc
	v_cmp_lt_i32_e32 vcc, 0, v225
	v_add_u32_e32 v249, 0xfff, v225
	s_nop 0
	v_cndmask_b32_e32 v248, v1, v0, vcc
	v_cmp_eq_u32_e32 vcc, 0, v225
	v_mul_f32_e32 v107, v248, v107
	s_nop 0
	v_cndmask_b32_e32 v107, v107, v246, vcc
	v_cmp_gt_u32_e32 vcc, 0x1fff, v249
	s_nop 1
	v_cndmask_b32_e32 v107, 0, v107, vcc
	v_cmp_lt_i32_e32 vcc, 0, v226
	v_add_u32_e32 v249, 0xfff, v226
	s_nop 0
	v_cndmask_b32_e32 v248, v1, v0, vcc
	v_cmp_eq_u32_e32 vcc, 0, v226
	v_mul_f32_e32 v108, v248, v108
	s_nop 0
	v_cndmask_b32_e32 v108, v108, v246, vcc
	v_cmp_gt_u32_e32 vcc, 0x1fff, v249
	s_nop 1
	v_cndmask_b32_e32 v108, 0, v108, vcc
	v_cmp_lt_i32_e32 vcc, 0, v227
	v_add_u32_e32 v249, 0xfff, v227
	s_nop 0
	v_cndmask_b32_e32 v248, v1, v0, vcc
	v_cmp_eq_u32_e32 vcc, 0, v227
	v_mul_f32_e32 v109, v248, v109
	s_nop 0
	v_cndmask_b32_e32 v109, v109, v246, vcc
	v_cmp_gt_u32_e32 vcc, 0x1fff, v249
	s_nop 1
	v_cndmask_b32_e32 v109, 0, v109, vcc
	v_cmp_lt_i32_e32 vcc, 0, v228
	v_add_u32_e32 v249, 0xfff, v228
	s_nop 0
	v_cndmask_b32_e32 v248, v1, v0, vcc
	v_cmp_eq_u32_e32 vcc, 0, v228
	v_mul_f32_e32 v110, v248, v110
	s_nop 0
	v_cndmask_b32_e32 v110, v110, v246, vcc
	v_cmp_gt_u32_e32 vcc, 0x1fff, v249
	s_nop 1
	v_cndmask_b32_e32 v110, 0, v110, vcc
	v_cmp_lt_i32_e32 vcc, 0, v229
	v_add_u32_e32 v249, 0xfff, v229
	s_nop 0
	v_cndmask_b32_e32 v248, v1, v0, vcc
	v_cmp_eq_u32_e32 vcc, 0, v229
	v_mul_f32_e32 v111, v248, v111
	s_nop 0
	v_cndmask_b32_e32 v111, v111, v246, vcc
	v_cmp_gt_u32_e32 vcc, 0x1fff, v249
	s_nop 1
	v_cndmask_b32_e32 v111, 0, v111, vcc
	v_cmp_lt_i32_e32 vcc, 0, v230
	v_add_u32_e32 v249, 0xfff, v230
	s_nop 0
	v_cndmask_b32_e32 v248, v1, v0, vcc
	v_cmp_eq_u32_e32 vcc, 0, v230
	v_mul_f32_e32 v122, v248, v122
	s_nop 0
	v_cndmask_b32_e32 v122, v122, v246, vcc
	v_cmp_gt_u32_e32 vcc, 0x1fff, v249
	s_nop 1
	v_cndmask_b32_e32 v122, 0, v122, vcc
	v_cmp_lt_i32_e32 vcc, 0, v231
	v_add_u32_e32 v249, 0xfff, v231
	s_nop 0
	v_cndmask_b32_e32 v248, v1, v0, vcc
	v_cmp_eq_u32_e32 vcc, 0, v231
	v_mul_f32_e32 v123, v248, v123
	s_nop 0
	v_cndmask_b32_e32 v123, v123, v246, vcc
	v_cmp_gt_u32_e32 vcc, 0x1fff, v249
	s_nop 1
	v_cndmask_b32_e32 v123, 0, v123, vcc
	v_cmp_lt_i32_e32 vcc, 0, v232
	v_add_u32_e32 v249, 0xfff, v232
	s_nop 0
	v_cndmask_b32_e32 v248, v1, v0, vcc
	v_cmp_eq_u32_e32 vcc, 0, v232
	v_mul_f32_e32 v124, v248, v124
	s_nop 0
	v_cndmask_b32_e32 v124, v124, v246, vcc
	v_cmp_gt_u32_e32 vcc, 0x1fff, v249
	s_nop 1
	v_cndmask_b32_e32 v124, 0, v124, vcc
	v_cmp_lt_i32_e32 vcc, 0, v233
	v_add_u32_e32 v249, 0xfff, v233
	s_nop 0
	v_cndmask_b32_e32 v248, v1, v0, vcc
	v_cmp_eq_u32_e32 vcc, 0, v233
	v_mul_f32_e32 v125, v248, v125
	s_nop 0
	v_cndmask_b32_e32 v125, v125, v246, vcc
	v_cmp_gt_u32_e32 vcc, 0x1fff, v249
	s_nop 1
	v_cndmask_b32_e32 v125, 0, v125, vcc
	v_cmp_lt_i32_e32 vcc, 0, v234
	v_add_u32_e32 v249, 0xfff, v234
	s_nop 0
	v_cndmask_b32_e32 v248, v1, v0, vcc
	v_cmp_eq_u32_e32 vcc, 0, v234
	v_mul_f32_e32 v126, v248, v126
	s_nop 0
	v_cndmask_b32_e32 v126, v126, v246, vcc
	v_cmp_gt_u32_e32 vcc, 0x1fff, v249
	s_nop 1
	v_cndmask_b32_e32 v126, 0, v126, vcc
	v_cmp_lt_i32_e32 vcc, 0, v235
	v_add_u32_e32 v249, 0xfff, v235
	s_nop 0
	v_cndmask_b32_e32 v248, v1, v0, vcc
	v_cmp_eq_u32_e32 vcc, 0, v235
	v_mul_f32_e32 v127, v248, v127
	s_nop 0
	v_cndmask_b32_e32 v127, v127, v246, vcc
	v_cmp_gt_u32_e32 vcc, 0x1fff, v249
	s_nop 1
	v_cndmask_b32_e32 v127, 0, v127, vcc
	v_cvt_pk_bf16_f32 v142, v95, v96
	v_cvt_pk_bf16_f32 v143, v97, v98
	v_cvt_pk_bf16_f32 v144, v99, v100
	v_cvt_pk_bf16_f32 v145, v101, v102
	v_cvt_pk_bf16_f32 v146, v103, v104
	v_cvt_pk_bf16_f32 v147, v105, v106
	v_cvt_pk_bf16_f32 v148, v107, v108
	v_cvt_pk_bf16_f32 v149, v109, v110
	v_cvt_pk_bf16_f32 v150, v111, v122
	v_cvt_pk_bf16_f32 v151, v123, v124
	v_cvt_pk_bf16_f32 v152, v97, v98
	v_cvt_pk_bf16_f32 v153, v99, v100
	v_cvt_pk_bf16_f32 v154, v101, v102
	v_cvt_pk_bf16_f32 v155, v103, v104
	v_cvt_pk_bf16_f32 v156, v105, v106
	v_cvt_pk_bf16_f32 v157, v107, v108
	v_cvt_pk_bf16_f32 v158, v109, v110
	v_cvt_pk_bf16_f32 v159, v111, v122
	v_cvt_pk_bf16_f32 v160, v123, v124
	v_cvt_pk_bf16_f32 v161, v125, v126
	v_cvt_pk_bf16_f32 v236, v96, v97
	v_cvt_pk_bf16_f32 v237, v98, v99
	v_cvt_pk_bf16_f32 v238, v100, v101
	v_cvt_pk_bf16_f32 v239, v102, v103
	v_cvt_pk_bf16_f32 v240, v104, v105
	v_cvt_pk_bf16_f32 v241, v106, v107
	v_cvt_pk_bf16_f32 v242, v108, v109
	v_cvt_pk_bf16_f32 v243, v110, v111
	v_cvt_pk_bf16_f32 v244, v122, v123
	v_cvt_pk_bf16_f32 v245, v124, v125
	v_cvt_pk_bf16_f32 v170, v98, v99
	v_cvt_pk_bf16_f32 v171, v100, v101
	v_cvt_pk_bf16_f32 v172, v102, v103
	v_cvt_pk_bf16_f32 v173, v104, v105
	v_cvt_pk_bf16_f32 v174, v106, v107
	v_cvt_pk_bf16_f32 v175, v108, v109
	v_cvt_pk_bf16_f32 v176, v110, v111
	v_cvt_pk_bf16_f32 v177, v122, v123
	v_cvt_pk_bf16_f32 v178, v124, v125
	v_cvt_pk_bf16_f32 v179, v126, v127
	ds_write_b128 v251, v[142:145] offset:0
	ds_write_b128 v251, v[146:149] offset:16
	ds_write_b128 v251, v[236:239] offset:16400
	ds_write_b128 v251, v[240:243] offset:16416
	ds_write_b128 v251, v[152:155] offset:32848
	ds_write_b128 v251, v[156:159] offset:32864
	ds_write_b128 v251, v[170:173] offset:49296
	ds_write_b128 v251, v[174:177] offset:49312
	ds_write_b128 v162, v[144:147] offset:0
	ds_write_b128 v162, v[148:151] offset:16
	ds_write_b128 v162, v[238:241] offset:16512
	ds_write_b128 v162, v[242:245] offset:16528
	ds_write_b128 v162, v[154:157] offset:32960
	ds_write_b128 v162, v[158:161] offset:32976
	ds_write_b128 v162, v[172:175] offset:49408
	ds_write_b128 v162, v[176:179] offset:49424
	s_andn2_b64 vcc, exec, s[88:89]
	s_cbranch_vccnz .LBB0_721
	global_load_dwordx4 v[0:3], v[56:57], off
	v_add_u32_e32 v4, v17, v67
	s_waitcnt vmcnt(0)
	ds_write_b128 v4, v[0:3]
	global_load_dwordx4 v[0:3], v[58:59], off
	v_add_u32_e32 v4, v17, v66
	s_waitcnt vmcnt(0)
	ds_write_b128 v4, v[0:3]
